# mixer pool stage 2 rewritten: all PMT weight + scale loads issued up front (layers 0-2)
# baseline (speedup 1.0000x reference)
.LBB0_231:
	s_or_b64 exec, exec, s[0:1]
	s_ashr_i32 s29, s28, 31
	s_lshl_b64 s[0:1], s[28:29], 15
	v_lshl_add_u64 v[202:203], v[168:169], 0, s[0:1]
	s_ashr_i32 s35, s34, 31
	v_lshl_add_u64 v[228:229], s[34:35], 2, v[156:157]
	s_mov_b64 s[0:1], 0x2000
	v_lshl_add_u64 v[232:233], v[202:203], 0, s[0:1]
	s_mov_b64 s[0:1], 0x4000
	v_lshl_add_u64 v[224:225], v[202:203], 0, s[0:1]
	s_mov_b64 s[0:1], 0x6000
	v_lshl_add_u64 v[226:227], v[202:203], 0, s[0:1]
	global_load_dwordx4 v[178:181], v[228:229], off
	global_load_dwordx4 v[182:185], v[228:229], off offset:16
	global_load_dwordx4 v[186:189], v[228:229], off offset:128
	global_load_dwordx4 v[190:193], v[228:229], off offset:144
	global_load_dwordx4 v[194:197], v[228:229], off offset:256
	global_load_dwordx4 v[198:201], v[228:229], off offset:272
	global_load_dwordx4 v[216:219], v[228:229], off offset:384
	global_load_dwordx4 v[220:223], v[228:229], off offset:400
	global_load_dwordx4 v[16:19], v[202:203], off
	global_load_dwordx4 v[20:23], v[202:203], off offset:64
	global_load_dwordx4 v[24:27], v[202:203], off offset:128
	global_load_dwordx4 v[28:31], v[202:203], off offset:192
	global_load_dwordx4 v[32:35], v[202:203], off offset:1024
	global_load_dwordx4 v[36:39], v[202:203], off offset:1088
	global_load_dwordx4 v[40:43], v[202:203], off offset:1152
	global_load_dwordx4 v[44:47], v[202:203], off offset:1216
	global_load_dwordx4 v[48:51], v[232:233], off
	global_load_dwordx4 v[52:55], v[232:233], off offset:64
	global_load_dwordx4 v[56:59], v[232:233], off offset:128
	global_load_dwordx4 v[60:63], v[232:233], off offset:192
	global_load_dwordx4 v[64:67], v[232:233], off offset:1024
	global_load_dwordx4 v[68:71], v[232:233], off offset:1088
	global_load_dwordx4 v[72:75], v[232:233], off offset:1152
	global_load_dwordx4 v[76:79], v[232:233], off offset:1216
	global_load_dwordx4 v[80:83], v[224:225], off
	global_load_dwordx4 v[84:87], v[224:225], off offset:64
	global_load_dwordx4 v[88:91], v[224:225], off offset:128
	global_load_dwordx4 v[92:95], v[224:225], off offset:192
	global_load_dwordx4 v[96:99], v[224:225], off offset:1024
	global_load_dwordx4 v[100:103], v[224:225], off offset:1088
	global_load_dwordx4 v[104:107], v[224:225], off offset:1152
	global_load_dwordx4 v[108:111], v[224:225], off offset:1216
	global_load_dwordx4 v[112:115], v[226:227], off
	global_load_dwordx4 v[116:119], v[226:227], off offset:64
	global_load_dwordx4 v[120:123], v[226:227], off offset:128
	global_load_dwordx4 v[124:127], v[226:227], off offset:192
	global_load_dwordx4 v[128:131], v[226:227], off offset:1024
	global_load_dwordx4 v[132:135], v[226:227], off offset:1088
	global_load_dwordx4 v[136:139], v[226:227], off offset:1152
	global_load_dwordx4 v[174:177], v[226:227], off offset:1216
	v_readlane_b32 s0, v235, 47
	v_readlane_b32 s1, v235, 48
	s_waitcnt lgkmcnt(0)
	ds_read_b128 v[0:3], v207
	ds_read_b128 v[4:7], v207 offset:64
	ds_read_b128 v[8:11], v207 offset:128
	ds_read_b128 v[12:15], v207 offset:192
	v_or_b32_e32 v242, s21, v204
	v_ashrrev_i32_e32 v243, 31, v242
	v_lshlrev_b64 v[242:243], 11, v[242:243]
	v_lshl_add_u64 v[242:243], s[0:1], 0, v[242:243]
	v_lshl_add_u64 v[242:243], s[34:35], 1, v[242:243]
	v_lshl_add_u64 v[244:245], v[154:155], 1, v[242:243]
	v_xor_b32_e32 v242, 16, v213
	v_xor_b32_e32 v243, 32, v213
	v_lshlrev_b32_e32 v242, 2, v242
	v_lshlrev_b32_e32 v243, 2, v243
	s_waitcnt lgkmcnt(0)
	s_waitcnt vmcnt(28)
	v_mfma_f32_16x16x32_bf16 v[16:19], v[16:19], v[0:3], 0
	v_mfma_f32_16x16x32_bf16 v[16:19], v[20:23], v[4:7], v[16:19]
	v_mfma_f32_16x16x32_bf16 v[16:19], v[24:27], v[8:11], v[16:19]
	v_mfma_f32_16x16x32_bf16 v[16:19], v[28:31], v[12:15], v[16:19]
	s_waitcnt vmcnt(24)
	v_mfma_f32_16x16x32_bf16 v[32:35], v[32:35], v[0:3], 0
	v_mfma_f32_16x16x32_bf16 v[32:35], v[36:39], v[4:7], v[32:35]
	v_mfma_f32_16x16x32_bf16 v[32:35], v[40:43], v[8:11], v[32:35]
	v_mfma_f32_16x16x32_bf16 v[32:35], v[44:47], v[12:15], v[32:35]
	s_waitcnt vmcnt(20)
	v_mfma_f32_16x16x32_bf16 v[48:51], v[48:51], v[0:3], 0
	v_mfma_f32_16x16x32_bf16 v[48:51], v[52:55], v[4:7], v[48:51]
	v_mfma_f32_16x16x32_bf16 v[48:51], v[56:59], v[8:11], v[48:51]
	v_mfma_f32_16x16x32_bf16 v[48:51], v[60:63], v[12:15], v[48:51]
	s_waitcnt vmcnt(16)
	v_mfma_f32_16x16x32_bf16 v[64:67], v[64:67], v[0:3], 0
	v_mfma_f32_16x16x32_bf16 v[64:67], v[68:71], v[4:7], v[64:67]
	v_mfma_f32_16x16x32_bf16 v[64:67], v[72:75], v[8:11], v[64:67]
	v_mfma_f32_16x16x32_bf16 v[64:67], v[76:79], v[12:15], v[64:67]
	s_waitcnt vmcnt(12)
	v_mfma_f32_16x16x32_bf16 v[80:83], v[80:83], v[0:3], 0
	v_mfma_f32_16x16x32_bf16 v[80:83], v[84:87], v[4:7], v[80:83]
	v_mfma_f32_16x16x32_bf16 v[80:83], v[88:91], v[8:11], v[80:83]
	v_mfma_f32_16x16x32_bf16 v[80:83], v[92:95], v[12:15], v[80:83]
	s_waitcnt vmcnt(8)
	v_mfma_f32_16x16x32_bf16 v[96:99], v[96:99], v[0:3], 0
	v_mfma_f32_16x16x32_bf16 v[96:99], v[100:103], v[4:7], v[96:99]
	v_mfma_f32_16x16x32_bf16 v[96:99], v[104:107], v[8:11], v[96:99]
	v_mfma_f32_16x16x32_bf16 v[96:99], v[108:111], v[12:15], v[96:99]
	s_waitcnt vmcnt(4)
	v_mfma_f32_16x16x32_bf16 v[112:115], v[112:115], v[0:3], 0
	v_mfma_f32_16x16x32_bf16 v[112:115], v[116:119], v[4:7], v[112:115]
	v_mfma_f32_16x16x32_bf16 v[112:115], v[120:123], v[8:11], v[112:115]
	v_mfma_f32_16x16x32_bf16 v[112:115], v[124:127], v[12:15], v[112:115]
	s_waitcnt vmcnt(0)
	v_mfma_f32_16x16x32_bf16 v[128:131], v[128:131], v[0:3], 0
	v_mfma_f32_16x16x32_bf16 v[128:131], v[132:135], v[4:7], v[128:131]
	v_mfma_f32_16x16x32_bf16 v[128:131], v[136:139], v[8:11], v[128:131]
	v_mfma_f32_16x16x32_bf16 v[128:131], v[174:177], v[12:15], v[128:131]
	s_nop 7
	v_pk_mul_f32 v[16:17], v[16:17], v[178:179]
	v_pk_mul_f32 v[18:19], v[18:19], v[180:181]
	v_pk_mul_f32 v[230:231], v[16:17], v[16:17]
	v_pk_mul_f32 v[236:237], v[18:19], v[18:19]
	v_pk_mul_f32 v[32:33], v[32:33], v[182:183]
	v_pk_mul_f32 v[34:35], v[34:35], v[184:185]
	v_pk_fma_f32 v[230:231], v[32:33], v[32:33], v[230:231]
	v_pk_fma_f32 v[236:237], v[34:35], v[34:35], v[236:237]
	v_pk_mul_f32 v[48:49], v[48:49], v[186:187]
	v_pk_mul_f32 v[50:51], v[50:51], v[188:189]
	v_pk_fma_f32 v[230:231], v[48:49], v[48:49], v[230:231]
	v_pk_fma_f32 v[236:237], v[50:51], v[50:51], v[236:237]
	v_pk_mul_f32 v[64:65], v[64:65], v[190:191]
	v_pk_mul_f32 v[66:67], v[66:67], v[192:193]
	v_pk_fma_f32 v[230:231], v[64:65], v[64:65], v[230:231]
	v_pk_fma_f32 v[236:237], v[66:67], v[66:67], v[236:237]
	v_pk_mul_f32 v[80:81], v[80:81], v[194:195]
	v_pk_mul_f32 v[82:83], v[82:83], v[196:197]
	v_pk_fma_f32 v[230:231], v[80:81], v[80:81], v[230:231]
	v_pk_fma_f32 v[236:237], v[82:83], v[82:83], v[236:237]
	v_pk_mul_f32 v[96:97], v[96:97], v[198:199]
	v_pk_mul_f32 v[98:99], v[98:99], v[200:201]
	v_pk_fma_f32 v[230:231], v[96:97], v[96:97], v[230:231]
	v_pk_fma_f32 v[236:237], v[98:99], v[98:99], v[236:237]
	v_pk_mul_f32 v[112:113], v[112:113], v[216:217]
	v_pk_mul_f32 v[114:115], v[114:115], v[218:219]
	v_pk_fma_f32 v[230:231], v[112:113], v[112:113], v[230:231]
	v_pk_fma_f32 v[236:237], v[114:115], v[114:115], v[236:237]
	v_pk_mul_f32 v[128:129], v[128:129], v[220:221]
	v_pk_mul_f32 v[130:131], v[130:131], v[222:223]
	v_pk_fma_f32 v[230:231], v[128:129], v[128:129], v[230:231]
	v_pk_fma_f32 v[236:237], v[130:131], v[130:131], v[236:237]
	v_pk_add_f32 v[230:231], v[230:231], v[236:237]
	s_nop 0
	v_add_f32_e32 v240, v230, v231
	s_nop 0
	ds_bpermute_b32 v241, v242, v240
	s_waitcnt lgkmcnt(0)
	v_add_f32_e32 v240, v240, v241
	s_nop 0
	ds_bpermute_b32 v241, v243, v240
	s_waitcnt lgkmcnt(0)
	v_add_f32_e32 v240, v240, v241
	v_fmamk_f32 v240, v240, 0x3c000000, v151
	v_cmp_gt_f32_e32 vcc, s20, v240
	v_mul_f32_e32 v241, 0x4b800000, v240
	s_nop 1
	v_cndmask_b32_e32 v240, v240, v241, vcc
	v_rsq_f32_e32 v240, v240
	s_nop 0
	v_mul_f32_e32 v241, 0x45800000, v240
	v_cndmask_b32_e32 v238, v240, v241, vcc
	v_mov_b32_e32 v239, v238
	v_pk_mul_f32 v[16:17], v[16:17], v[238:239]
	v_pk_mul_f32 v[18:19], v[18:19], v[238:239]
	v_pk_mul_f32 v[32:33], v[32:33], v[238:239]
	v_pk_mul_f32 v[34:35], v[34:35], v[238:239]
	v_cvt_pk_bf16_f32 v20, v16, v17
	v_cvt_pk_bf16_f32 v21, v18, v19
	v_cvt_pk_bf16_f32 v22, v32, v33
	v_cvt_pk_bf16_f32 v23, v34, v35
	global_store_dwordx4 v[244:245], v[20:23], off
	v_pk_mul_f32 v[48:49], v[48:49], v[238:239]
	v_pk_mul_f32 v[50:51], v[50:51], v[238:239]
	v_pk_mul_f32 v[64:65], v[64:65], v[238:239]
	v_pk_mul_f32 v[66:67], v[66:67], v[238:239]
	v_cvt_pk_bf16_f32 v52, v48, v49
	v_cvt_pk_bf16_f32 v53, v50, v51
	v_cvt_pk_bf16_f32 v54, v64, v65
	v_cvt_pk_bf16_f32 v55, v66, v67
	global_store_dwordx4 v[244:245], v[52:55], off offset:64
	v_pk_mul_f32 v[80:81], v[80:81], v[238:239]
	v_pk_mul_f32 v[82:83], v[82:83], v[238:239]
	v_pk_mul_f32 v[96:97], v[96:97], v[238:239]
	v_pk_mul_f32 v[98:99], v[98:99], v[238:239]
	v_cvt_pk_bf16_f32 v84, v80, v81
	v_cvt_pk_bf16_f32 v85, v82, v83
	v_cvt_pk_bf16_f32 v86, v96, v97
	v_cvt_pk_bf16_f32 v87, v98, v99
	global_store_dwordx4 v[244:245], v[84:87], off offset:128
	v_pk_mul_f32 v[112:113], v[112:113], v[238:239]
	v_pk_mul_f32 v[114:115], v[114:115], v[238:239]
	v_pk_mul_f32 v[128:129], v[128:129], v[238:239]
	v_pk_mul_f32 v[130:131], v[130:131], v[238:239]
	v_cvt_pk_bf16_f32 v116, v112, v113
	v_cvt_pk_bf16_f32 v117, v114, v115
	v_cvt_pk_bf16_f32 v118, v128, v129
	v_cvt_pk_bf16_f32 v119, v130, v131
	global_store_dwordx4 v[244:245], v[116:119], off offset:192
	s_waitcnt lgkmcnt(0)

.LBB0_939:
	s_or_b64 exec, exec, s[0:1]
	s_ashr_i32 s7, s6, 31
	s_lshl_b64 s[0:1], s[6:7], 15
	v_lshl_add_u64 v[204:205], v[170:171], 0, s[0:1]
	s_ashr_i32 s9, s8, 31
	v_lshl_add_u64 v[232:233], s[8:9], 2, v[158:159]
	s_mov_b64 s[0:1], 0x2000
	v_lshl_add_u64 v[226:227], v[204:205], 0, s[0:1]
	s_mov_b64 s[0:1], 0x4000
	v_lshl_add_u64 v[228:229], v[204:205], 0, s[0:1]
	s_mov_b64 s[0:1], 0x6000
	v_lshl_add_u64 v[230:231], v[204:205], 0, s[0:1]
	global_load_dwordx4 v[180:183], v[232:233], off offset:2048
	global_load_dwordx4 v[184:187], v[232:233], off offset:2064
	global_load_dwordx4 v[188:191], v[232:233], off offset:2176
	global_load_dwordx4 v[192:195], v[232:233], off offset:2192
	global_load_dwordx4 v[196:199], v[232:233], off offset:2304
	global_load_dwordx4 v[200:203], v[232:233], off offset:2320
	global_load_dwordx4 v[218:221], v[232:233], off offset:2432
	global_load_dwordx4 v[222:225], v[232:233], off offset:2448
	global_load_dwordx4 v[16:19], v[204:205], off
	global_load_dwordx4 v[20:23], v[204:205], off offset:64
	global_load_dwordx4 v[24:27], v[204:205], off offset:128
	global_load_dwordx4 v[28:31], v[204:205], off offset:192
	global_load_dwordx4 v[32:35], v[204:205], off offset:1024
	global_load_dwordx4 v[36:39], v[204:205], off offset:1088
	global_load_dwordx4 v[40:43], v[204:205], off offset:1152
	global_load_dwordx4 v[44:47], v[204:205], off offset:1216
	global_load_dwordx4 v[48:51], v[226:227], off
	global_load_dwordx4 v[52:55], v[226:227], off offset:64
	global_load_dwordx4 v[56:59], v[226:227], off offset:128
	global_load_dwordx4 v[60:63], v[226:227], off offset:192
	global_load_dwordx4 v[64:67], v[226:227], off offset:1024
	global_load_dwordx4 v[68:71], v[226:227], off offset:1088
	global_load_dwordx4 v[72:75], v[226:227], off offset:1152
	global_load_dwordx4 v[76:79], v[226:227], off offset:1216
	global_load_dwordx4 v[80:83], v[228:229], off
	global_load_dwordx4 v[84:87], v[228:229], off offset:64
	global_load_dwordx4 v[88:91], v[228:229], off offset:128
	global_load_dwordx4 v[92:95], v[228:229], off offset:192
	global_load_dwordx4 v[96:99], v[228:229], off offset:1024
	global_load_dwordx4 v[100:103], v[228:229], off offset:1088
	global_load_dwordx4 v[104:107], v[228:229], off offset:1152
	global_load_dwordx4 v[108:111], v[228:229], off offset:1216
	global_load_dwordx4 v[112:115], v[230:231], off
	global_load_dwordx4 v[116:119], v[230:231], off offset:64
	global_load_dwordx4 v[120:123], v[230:231], off offset:128
	global_load_dwordx4 v[124:127], v[230:231], off offset:192
	global_load_dwordx4 v[128:131], v[230:231], off offset:1024
	global_load_dwordx4 v[132:135], v[230:231], off offset:1088
	global_load_dwordx4 v[136:139], v[230:231], off offset:1152
	global_load_dwordx4 v[176:179], v[230:231], off offset:1216
	v_readlane_b32 s0, v235, 47
	v_readlane_b32 s1, v235, 48
	s_waitcnt lgkmcnt(0)
	ds_read_b128 v[0:3], v209
	ds_read_b128 v[4:7], v209 offset:64
	ds_read_b128 v[8:11], v209 offset:128
	ds_read_b128 v[12:15], v209 offset:192
	v_or_b32_e32 v244, s29, v206
	v_ashrrev_i32_e32 v245, 31, v244
	v_lshlrev_b64 v[244:245], 11, v[244:245]
	v_lshl_add_u64 v[244:245], s[0:1], 0, v[244:245]
	v_lshl_add_u64 v[244:245], s[8:9], 1, v[244:245]
	v_lshl_add_u64 v[246:247], v[156:157], 1, v[244:245]
	v_xor_b32_e32 v244, 16, v216
	v_xor_b32_e32 v245, 32, v216
	v_lshlrev_b32_e32 v244, 2, v244
	v_lshlrev_b32_e32 v245, 2, v245
	s_waitcnt lgkmcnt(0)
	s_waitcnt vmcnt(28)
	v_mfma_f32_16x16x32_bf16 v[16:19], v[16:19], v[0:3], 0
	v_mfma_f32_16x16x32_bf16 v[16:19], v[20:23], v[4:7], v[16:19]
	v_mfma_f32_16x16x32_bf16 v[16:19], v[24:27], v[8:11], v[16:19]
	v_mfma_f32_16x16x32_bf16 v[16:19], v[28:31], v[12:15], v[16:19]
	s_waitcnt vmcnt(24)
	v_mfma_f32_16x16x32_bf16 v[32:35], v[32:35], v[0:3], 0
	v_mfma_f32_16x16x32_bf16 v[32:35], v[36:39], v[4:7], v[32:35]
	v_mfma_f32_16x16x32_bf16 v[32:35], v[40:43], v[8:11], v[32:35]
	v_mfma_f32_16x16x32_bf16 v[32:35], v[44:47], v[12:15], v[32:35]
	s_waitcnt vmcnt(20)
	v_mfma_f32_16x16x32_bf16 v[48:51], v[48:51], v[0:3], 0
	v_mfma_f32_16x16x32_bf16 v[48:51], v[52:55], v[4:7], v[48:51]
	v_mfma_f32_16x16x32_bf16 v[48:51], v[56:59], v[8:11], v[48:51]
	v_mfma_f32_16x16x32_bf16 v[48:51], v[60:63], v[12:15], v[48:51]
	s_waitcnt vmcnt(16)
	v_mfma_f32_16x16x32_bf16 v[64:67], v[64:67], v[0:3], 0
	v_mfma_f32_16x16x32_bf16 v[64:67], v[68:71], v[4:7], v[64:67]
	v_mfma_f32_16x16x32_bf16 v[64:67], v[72:75], v[8:11], v[64:67]
	v_mfma_f32_16x16x32_bf16 v[64:67], v[76:79], v[12:15], v[64:67]
	s_waitcnt vmcnt(12)
	v_mfma_f32_16x16x32_bf16 v[80:83], v[80:83], v[0:3], 0
	v_mfma_f32_16x16x32_bf16 v[80:83], v[84:87], v[4:7], v[80:83]
	v_mfma_f32_16x16x32_bf16 v[80:83], v[88:91], v[8:11], v[80:83]
	v_mfma_f32_16x16x32_bf16 v[80:83], v[92:95], v[12:15], v[80:83]
	s_waitcnt vmcnt(8)
	v_mfma_f32_16x16x32_bf16 v[96:99], v[96:99], v[0:3], 0
	v_mfma_f32_16x16x32_bf16 v[96:99], v[100:103], v[4:7], v[96:99]
	v_mfma_f32_16x16x32_bf16 v[96:99], v[104:107], v[8:11], v[96:99]
	v_mfma_f32_16x16x32_bf16 v[96:99], v[108:111], v[12:15], v[96:99]
	s_waitcnt vmcnt(4)
	v_mfma_f32_16x16x32_bf16 v[112:115], v[112:115], v[0:3], 0
	v_mfma_f32_16x16x32_bf16 v[112:115], v[116:119], v[4:7], v[112:115]
	v_mfma_f32_16x16x32_bf16 v[112:115], v[120:123], v[8:11], v[112:115]
	v_mfma_f32_16x16x32_bf16 v[112:115], v[124:127], v[12:15], v[112:115]
	s_waitcnt vmcnt(0)
	v_mfma_f32_16x16x32_bf16 v[128:131], v[128:131], v[0:3], 0
	v_mfma_f32_16x16x32_bf16 v[128:131], v[132:135], v[4:7], v[128:131]
	v_mfma_f32_16x16x32_bf16 v[128:131], v[136:139], v[8:11], v[128:131]
	v_mfma_f32_16x16x32_bf16 v[128:131], v[176:179], v[12:15], v[128:131]
	s_nop 7
	v_pk_mul_f32 v[16:17], v[16:17], v[180:181]
	v_pk_mul_f32 v[18:19], v[18:19], v[182:183]
	v_pk_mul_f32 v[236:237], v[16:17], v[16:17]
	v_pk_mul_f32 v[238:239], v[18:19], v[18:19]
	v_pk_mul_f32 v[32:33], v[32:33], v[184:185]
	v_pk_mul_f32 v[34:35], v[34:35], v[186:187]
	v_pk_fma_f32 v[236:237], v[32:33], v[32:33], v[236:237]
	v_pk_fma_f32 v[238:239], v[34:35], v[34:35], v[238:239]
	v_pk_mul_f32 v[48:49], v[48:49], v[188:189]
	v_pk_mul_f32 v[50:51], v[50:51], v[190:191]
	v_pk_fma_f32 v[236:237], v[48:49], v[48:49], v[236:237]
	v_pk_fma_f32 v[238:239], v[50:51], v[50:51], v[238:239]
	v_pk_mul_f32 v[64:65], v[64:65], v[192:193]
	v_pk_mul_f32 v[66:67], v[66:67], v[194:195]
	v_pk_fma_f32 v[236:237], v[64:65], v[64:65], v[236:237]
	v_pk_fma_f32 v[238:239], v[66:67], v[66:67], v[238:239]
	v_pk_mul_f32 v[80:81], v[80:81], v[196:197]
	v_pk_mul_f32 v[82:83], v[82:83], v[198:199]
	v_pk_fma_f32 v[236:237], v[80:81], v[80:81], v[236:237]
	v_pk_fma_f32 v[238:239], v[82:83], v[82:83], v[238:239]
	v_pk_mul_f32 v[96:97], v[96:97], v[200:201]
	v_pk_mul_f32 v[98:99], v[98:99], v[202:203]
	v_pk_fma_f32 v[236:237], v[96:97], v[96:97], v[236:237]
	v_pk_fma_f32 v[238:239], v[98:99], v[98:99], v[238:239]
	v_pk_mul_f32 v[112:113], v[112:113], v[218:219]
	v_pk_mul_f32 v[114:115], v[114:115], v[220:221]
	v_pk_fma_f32 v[236:237], v[112:113], v[112:113], v[236:237]
	v_pk_fma_f32 v[238:239], v[114:115], v[114:115], v[238:239]
	v_pk_mul_f32 v[128:129], v[128:129], v[222:223]
	v_pk_mul_f32 v[130:131], v[130:131], v[224:225]
	v_pk_fma_f32 v[236:237], v[128:129], v[128:129], v[236:237]
	v_pk_fma_f32 v[238:239], v[130:131], v[130:131], v[238:239]
	v_pk_add_f32 v[236:237], v[236:237], v[238:239]
	s_nop 0
	v_add_f32_e32 v242, v236, v237
	s_nop 0
	ds_bpermute_b32 v243, v244, v242
	s_waitcnt lgkmcnt(0)
	v_add_f32_e32 v242, v242, v243
	s_nop 0
	ds_bpermute_b32 v243, v245, v242
	s_waitcnt lgkmcnt(0)
	v_add_f32_e32 v242, v242, v243
	v_fmamk_f32 v242, v242, 0x3c000000, v153
	v_cmp_gt_f32_e32 vcc, s28, v242
	v_mul_f32_e32 v243, 0x4b800000, v242
	s_nop 1
	v_cndmask_b32_e32 v242, v242, v243, vcc
	v_rsq_f32_e32 v242, v242
	s_nop 0
	v_mul_f32_e32 v243, 0x45800000, v242
	v_cndmask_b32_e32 v240, v242, v243, vcc
	v_mov_b32_e32 v241, v240
	v_pk_mul_f32 v[16:17], v[16:17], v[240:241]
	v_pk_mul_f32 v[18:19], v[18:19], v[240:241]
	v_pk_mul_f32 v[32:33], v[32:33], v[240:241]
	v_pk_mul_f32 v[34:35], v[34:35], v[240:241]
	v_cvt_pk_bf16_f32 v20, v16, v17
	v_cvt_pk_bf16_f32 v21, v18, v19
	v_cvt_pk_bf16_f32 v22, v32, v33
	v_cvt_pk_bf16_f32 v23, v34, v35
	global_store_dwordx4 v[246:247], v[20:23], off
	v_pk_mul_f32 v[48:49], v[48:49], v[240:241]
	v_pk_mul_f32 v[50:51], v[50:51], v[240:241]
	v_pk_mul_f32 v[64:65], v[64:65], v[240:241]
	v_pk_mul_f32 v[66:67], v[66:67], v[240:241]
	v_cvt_pk_bf16_f32 v52, v48, v49
	v_cvt_pk_bf16_f32 v53, v50, v51
	v_cvt_pk_bf16_f32 v54, v64, v65
	v_cvt_pk_bf16_f32 v55, v66, v67
	global_store_dwordx4 v[246:247], v[52:55], off offset:64
	v_pk_mul_f32 v[80:81], v[80:81], v[240:241]
	v_pk_mul_f32 v[82:83], v[82:83], v[240:241]
	v_pk_mul_f32 v[96:97], v[96:97], v[240:241]
	v_pk_mul_f32 v[98:99], v[98:99], v[240:241]
	v_cvt_pk_bf16_f32 v84, v80, v81
	v_cvt_pk_bf16_f32 v85, v82, v83
	v_cvt_pk_bf16_f32 v86, v96, v97
	v_cvt_pk_bf16_f32 v87, v98, v99
	global_store_dwordx4 v[246:247], v[84:87], off offset:128
	v_pk_mul_f32 v[112:113], v[112:113], v[240:241]
	v_pk_mul_f32 v[114:115], v[114:115], v[240:241]
	v_pk_mul_f32 v[128:129], v[128:129], v[240:241]
	v_pk_mul_f32 v[130:131], v[130:131], v[240:241]
	v_cvt_pk_bf16_f32 v116, v112, v113
	v_cvt_pk_bf16_f32 v117, v114, v115
	v_cvt_pk_bf16_f32 v118, v128, v129
	v_cvt_pk_bf16_f32 v119, v130, v131
	global_store_dwordx4 v[246:247], v[116:119], off offset:192
	s_waitcnt lgkmcnt(0)

.LBB0_1648:
	s_or_b64 exec, exec, s[0:1]
	s_ashr_i32 s7, s6, 31
	s_lshl_b64 s[0:1], s[6:7], 15
	v_lshl_add_u64 v[204:205], v[170:171], 0, s[0:1]
	s_ashr_i32 s9, s8, 31
	v_lshl_add_u64 v[232:233], s[8:9], 2, v[158:159]
	s_mov_b64 s[0:1], 0x2000
	v_lshl_add_u64 v[226:227], v[204:205], 0, s[0:1]
	s_mov_b64 s[0:1], 0x4000
	v_lshl_add_u64 v[228:229], v[204:205], 0, s[0:1]
	s_mov_b64 s[0:1], 0x6000
	v_lshl_add_u64 v[230:231], v[204:205], 0, s[0:1]
	global_load_dwordx4 v[180:183], v[232:233], off
	global_load_dwordx4 v[184:187], v[232:233], off offset:16
	global_load_dwordx4 v[188:191], v[232:233], off offset:128
	global_load_dwordx4 v[192:195], v[232:233], off offset:144
	global_load_dwordx4 v[196:199], v[232:233], off offset:256
	global_load_dwordx4 v[200:203], v[232:233], off offset:272
	global_load_dwordx4 v[218:221], v[232:233], off offset:384
	global_load_dwordx4 v[222:225], v[232:233], off offset:400
	global_load_dwordx4 v[16:19], v[204:205], off
	global_load_dwordx4 v[20:23], v[204:205], off offset:64
	global_load_dwordx4 v[24:27], v[204:205], off offset:128
	global_load_dwordx4 v[28:31], v[204:205], off offset:192
	global_load_dwordx4 v[32:35], v[204:205], off offset:1024
	global_load_dwordx4 v[36:39], v[204:205], off offset:1088
	global_load_dwordx4 v[40:43], v[204:205], off offset:1152
	global_load_dwordx4 v[44:47], v[204:205], off offset:1216
	global_load_dwordx4 v[48:51], v[226:227], off
	global_load_dwordx4 v[52:55], v[226:227], off offset:64
	global_load_dwordx4 v[56:59], v[226:227], off offset:128
	global_load_dwordx4 v[60:63], v[226:227], off offset:192
	global_load_dwordx4 v[64:67], v[226:227], off offset:1024
	global_load_dwordx4 v[68:71], v[226:227], off offset:1088
	global_load_dwordx4 v[72:75], v[226:227], off offset:1152
	global_load_dwordx4 v[76:79], v[226:227], off offset:1216
	global_load_dwordx4 v[80:83], v[228:229], off
	global_load_dwordx4 v[84:87], v[228:229], off offset:64
	global_load_dwordx4 v[88:91], v[228:229], off offset:128
	global_load_dwordx4 v[92:95], v[228:229], off offset:192
	global_load_dwordx4 v[96:99], v[228:229], off offset:1024
	global_load_dwordx4 v[100:103], v[228:229], off offset:1088
	global_load_dwordx4 v[104:107], v[228:229], off offset:1152
	global_load_dwordx4 v[108:111], v[228:229], off offset:1216
	global_load_dwordx4 v[112:115], v[230:231], off
	global_load_dwordx4 v[116:119], v[230:231], off offset:64
	global_load_dwordx4 v[120:123], v[230:231], off offset:128
	global_load_dwordx4 v[124:127], v[230:231], off offset:192
	global_load_dwordx4 v[128:131], v[230:231], off offset:1024
	global_load_dwordx4 v[132:135], v[230:231], off offset:1088
	global_load_dwordx4 v[136:139], v[230:231], off offset:1152
	global_load_dwordx4 v[176:179], v[230:231], off offset:1216
	v_readlane_b32 s0, v235, 47
	v_readlane_b32 s1, v235, 48
	s_waitcnt lgkmcnt(0)
	ds_read_b128 v[0:3], v209
	ds_read_b128 v[4:7], v209 offset:64
	ds_read_b128 v[8:11], v209 offset:128
	ds_read_b128 v[12:15], v209 offset:192
	v_or_b32_e32 v244, s37, v206
	v_ashrrev_i32_e32 v245, 31, v244
	v_lshlrev_b64 v[244:245], 11, v[244:245]
	v_lshl_add_u64 v[244:245], s[0:1], 0, v[244:245]
	v_lshl_add_u64 v[244:245], s[8:9], 1, v[244:245]
	v_lshl_add_u64 v[246:247], v[156:157], 1, v[244:245]
	v_xor_b32_e32 v244, 16, v216
	v_xor_b32_e32 v245, 32, v216
	v_lshlrev_b32_e32 v244, 2, v244
	v_lshlrev_b32_e32 v245, 2, v245
	s_waitcnt lgkmcnt(0)
	s_waitcnt vmcnt(28)
	v_mfma_f32_16x16x32_bf16 v[16:19], v[16:19], v[0:3], 0
	v_mfma_f32_16x16x32_bf16 v[16:19], v[20:23], v[4:7], v[16:19]
	v_mfma_f32_16x16x32_bf16 v[16:19], v[24:27], v[8:11], v[16:19]
	v_mfma_f32_16x16x32_bf16 v[16:19], v[28:31], v[12:15], v[16:19]
	s_waitcnt vmcnt(24)
	v_mfma_f32_16x16x32_bf16 v[32:35], v[32:35], v[0:3], 0
	v_mfma_f32_16x16x32_bf16 v[32:35], v[36:39], v[4:7], v[32:35]
	v_mfma_f32_16x16x32_bf16 v[32:35], v[40:43], v[8:11], v[32:35]
	v_mfma_f32_16x16x32_bf16 v[32:35], v[44:47], v[12:15], v[32:35]
	s_waitcnt vmcnt(20)
	v_mfma_f32_16x16x32_bf16 v[48:51], v[48:51], v[0:3], 0
	v_mfma_f32_16x16x32_bf16 v[48:51], v[52:55], v[4:7], v[48:51]
	v_mfma_f32_16x16x32_bf16 v[48:51], v[56:59], v[8:11], v[48:51]
	v_mfma_f32_16x16x32_bf16 v[48:51], v[60:63], v[12:15], v[48:51]
	s_waitcnt vmcnt(16)
	v_mfma_f32_16x16x32_bf16 v[64:67], v[64:67], v[0:3], 0
	v_mfma_f32_16x16x32_bf16 v[64:67], v[68:71], v[4:7], v[64:67]
	v_mfma_f32_16x16x32_bf16 v[64:67], v[72:75], v[8:11], v[64:67]
	v_mfma_f32_16x16x32_bf16 v[64:67], v[76:79], v[12:15], v[64:67]
	s_waitcnt vmcnt(12)
	v_mfma_f32_16x16x32_bf16 v[80:83], v[80:83], v[0:3], 0
	v_mfma_f32_16x16x32_bf16 v[80:83], v[84:87], v[4:7], v[80:83]
	v_mfma_f32_16x16x32_bf16 v[80:83], v[88:91], v[8:11], v[80:83]
	v_mfma_f32_16x16x32_bf16 v[80:83], v[92:95], v[12:15], v[80:83]
	s_waitcnt vmcnt(8)
	v_mfma_f32_16x16x32_bf16 v[96:99], v[96:99], v[0:3], 0
	v_mfma_f32_16x16x32_bf16 v[96:99], v[100:103], v[4:7], v[96:99]
	v_mfma_f32_16x16x32_bf16 v[96:99], v[104:107], v[8:11], v[96:99]
	v_mfma_f32_16x16x32_bf16 v[96:99], v[108:111], v[12:15], v[96:99]
	s_waitcnt vmcnt(4)
	v_mfma_f32_16x16x32_bf16 v[112:115], v[112:115], v[0:3], 0
	v_mfma_f32_16x16x32_bf16 v[112:115], v[116:119], v[4:7], v[112:115]
	v_mfma_f32_16x16x32_bf16 v[112:115], v[120:123], v[8:11], v[112:115]
	v_mfma_f32_16x16x32_bf16 v[112:115], v[124:127], v[12:15], v[112:115]
	s_waitcnt vmcnt(0)
	v_mfma_f32_16x16x32_bf16 v[128:131], v[128:131], v[0:3], 0
	v_mfma_f32_16x16x32_bf16 v[128:131], v[132:135], v[4:7], v[128:131]
	v_mfma_f32_16x16x32_bf16 v[128:131], v[136:139], v[8:11], v[128:131]
	v_mfma_f32_16x16x32_bf16 v[128:131], v[176:179], v[12:15], v[128:131]
	s_nop 7
	v_pk_mul_f32 v[16:17], v[16:17], v[180:181]
	v_pk_mul_f32 v[18:19], v[18:19], v[182:183]
	v_pk_mul_f32 v[236:237], v[16:17], v[16:17]
	v_pk_mul_f32 v[238:239], v[18:19], v[18:19]
	v_pk_mul_f32 v[32:33], v[32:33], v[184:185]
	v_pk_mul_f32 v[34:35], v[34:35], v[186:187]
	v_pk_fma_f32 v[236:237], v[32:33], v[32:33], v[236:237]
	v_pk_fma_f32 v[238:239], v[34:35], v[34:35], v[238:239]
	v_pk_mul_f32 v[48:49], v[48:49], v[188:189]
	v_pk_mul_f32 v[50:51], v[50:51], v[190:191]
	v_pk_fma_f32 v[236:237], v[48:49], v[48:49], v[236:237]
	v_pk_fma_f32 v[238:239], v[50:51], v[50:51], v[238:239]
	v_pk_mul_f32 v[64:65], v[64:65], v[192:193]
	v_pk_mul_f32 v[66:67], v[66:67], v[194:195]
	v_pk_fma_f32 v[236:237], v[64:65], v[64:65], v[236:237]
	v_pk_fma_f32 v[238:239], v[66:67], v[66:67], v[238:239]
	v_pk_mul_f32 v[80:81], v[80:81], v[196:197]
	v_pk_mul_f32 v[82:83], v[82:83], v[198:199]
	v_pk_fma_f32 v[236:237], v[80:81], v[80:81], v[236:237]
	v_pk_fma_f32 v[238:239], v[82:83], v[82:83], v[238:239]
	v_pk_mul_f32 v[96:97], v[96:97], v[200:201]
	v_pk_mul_f32 v[98:99], v[98:99], v[202:203]
	v_pk_fma_f32 v[236:237], v[96:97], v[96:97], v[236:237]
	v_pk_fma_f32 v[238:239], v[98:99], v[98:99], v[238:239]
	v_pk_mul_f32 v[112:113], v[112:113], v[218:219]
	v_pk_mul_f32 v[114:115], v[114:115], v[220:221]
	v_pk_fma_f32 v[236:237], v[112:113], v[112:113], v[236:237]
	v_pk_fma_f32 v[238:239], v[114:115], v[114:115], v[238:239]
	v_pk_mul_f32 v[128:129], v[128:129], v[222:223]
	v_pk_mul_f32 v[130:131], v[130:131], v[224:225]
	v_pk_fma_f32 v[236:237], v[128:129], v[128:129], v[236:237]
	v_pk_fma_f32 v[238:239], v[130:131], v[130:131], v[238:239]
	v_pk_add_f32 v[236:237], v[236:237], v[238:239]
	s_nop 0
	v_add_f32_e32 v242, v236, v237
	s_nop 0
	ds_bpermute_b32 v243, v244, v242
	s_waitcnt lgkmcnt(0)
	v_add_f32_e32 v242, v242, v243
	s_nop 0
	ds_bpermute_b32 v243, v245, v242
	s_waitcnt lgkmcnt(0)
	v_add_f32_e32 v242, v242, v243
	v_fmamk_f32 v242, v242, 0x3c000000, v153
	v_cmp_gt_f32_e32 vcc, s36, v242
	v_mul_f32_e32 v243, 0x4b800000, v242
	s_nop 1
	v_cndmask_b32_e32 v242, v242, v243, vcc
	v_rsq_f32_e32 v242, v242
	s_nop 0
	v_mul_f32_e32 v243, 0x45800000, v242
	v_cndmask_b32_e32 v240, v242, v243, vcc
	v_mov_b32_e32 v241, v240
	v_pk_mul_f32 v[16:17], v[16:17], v[240:241]
	v_pk_mul_f32 v[18:19], v[18:19], v[240:241]
	v_pk_mul_f32 v[32:33], v[32:33], v[240:241]
	v_pk_mul_f32 v[34:35], v[34:35], v[240:241]
	v_cvt_pk_bf16_f32 v20, v16, v17
	v_cvt_pk_bf16_f32 v21, v18, v19
	v_cvt_pk_bf16_f32 v22, v32, v33
	v_cvt_pk_bf16_f32 v23, v34, v35
	global_store_dwordx4 v[246:247], v[20:23], off
	v_pk_mul_f32 v[48:49], v[48:49], v[240:241]
	v_pk_mul_f32 v[50:51], v[50:51], v[240:241]
	v_pk_mul_f32 v[64:65], v[64:65], v[240:241]
	v_pk_mul_f32 v[66:67], v[66:67], v[240:241]
	v_cvt_pk_bf16_f32 v52, v48, v49
	v_cvt_pk_bf16_f32 v53, v50, v51
	v_cvt_pk_bf16_f32 v54, v64, v65
	v_cvt_pk_bf16_f32 v55, v66, v67
	global_store_dwordx4 v[246:247], v[52:55], off offset:64
	v_pk_mul_f32 v[80:81], v[80:81], v[240:241]
	v_pk_mul_f32 v[82:83], v[82:83], v[240:241]
	v_pk_mul_f32 v[96:97], v[96:97], v[240:241]
	v_pk_mul_f32 v[98:99], v[98:99], v[240:241]
	v_cvt_pk_bf16_f32 v84, v80, v81
	v_cvt_pk_bf16_f32 v85, v82, v83
	v_cvt_pk_bf16_f32 v86, v96, v97
	v_cvt_pk_bf16_f32 v87, v98, v99
	global_store_dwordx4 v[246:247], v[84:87], off offset:128
	v_pk_mul_f32 v[112:113], v[112:113], v[240:241]
	v_pk_mul_f32 v[114:115], v[114:115], v[240:241]
	v_pk_mul_f32 v[128:129], v[128:129], v[240:241]
	v_pk_mul_f32 v[130:131], v[130:131], v[240:241]
	v_cvt_pk_bf16_f32 v116, v112, v113
	v_cvt_pk_bf16_f32 v117, v114, v115
	v_cvt_pk_bf16_f32 v118, v128, v129
	v_cvt_pk_bf16_f32 v119, v130, v131
	global_store_dwordx4 v[246:247], v[116:119], off offset:192
	s_waitcnt lgkmcnt(0)

	.amdhsa_kernel _Z14fwd_megakernel4Args
		.amdhsa_group_segment_fixed_size 0
		.amdhsa_private_segment_fixed_size 0
		.amdhsa_kernarg_size 432
		.amdhsa_user_sgpr_count 2
		.amdhsa_user_sgpr_dispatch_ptr 0
		.amdhsa_user_sgpr_queue_ptr 0
		.amdhsa_user_sgpr_kernarg_segment_ptr 1
		.amdhsa_user_sgpr_dispatch_id 0
		.amdhsa_user_sgpr_kernarg_preload_length 0
		.amdhsa_user_sgpr_kernarg_preload_offset 0
		.amdhsa_user_sgpr_private_segment_size 0
		.amdhsa_uses_dynamic_stack 0
		.amdhsa_enable_private_segment 0
		.amdhsa_system_sgpr_workgroup_id_x 1
		.amdhsa_system_sgpr_workgroup_id_y 0
		.amdhsa_system_sgpr_workgroup_id_z 0
		.amdhsa_system_sgpr_workgroup_info 0
		.amdhsa_system_vgpr_workitem_id 2
		.amdhsa_next_free_vgpr 256
		.amdhsa_next_free_sgpr 98
		.amdhsa_accum_offset 256
		.amdhsa_reserve_vcc 1
		.amdhsa_float_round_mode_32 0
		.amdhsa_float_round_mode_16_64 0
		.amdhsa_float_denorm_mode_32 3
		.amdhsa_float_denorm_mode_16_64 3
		.amdhsa_dx10_clamp 1
		.amdhsa_ieee_mode 1
		.amdhsa_fp16_overflow 0
		.amdhsa_tg_split 0
		.amdhsa_exception_fp_ieee_invalid_op 0
		.amdhsa_exception_fp_denorm_src 0
		.amdhsa_exception_fp_ieee_div_zero 0
		.amdhsa_exception_fp_ieee_overflow 0
		.amdhsa_exception_fp_ieee_underflow 0
		.amdhsa_exception_fp_ieee_inexact 0
		.amdhsa_exception_int_div_zero 0
	.end_amdhsa_kernel

amdhsa.kernels:
  - .agpr_count:     0
    .args:
      - .offset:         0
        .size:           176
        .value_kind:     by_value
      - .offset:         176
        .size:           4
        .value_kind:     hidden_block_count_x
      - .offset:         180
        .size:           4
        .value_kind:     hidden_block_count_y
      - .offset:         184
        .size:           4
        .value_kind:     hidden_block_count_z
      - .offset:         188
        .size:           2
        .value_kind:     hidden_group_size_x
      - .offset:         190
        .size:           2
        .value_kind:     hidden_group_size_y
      - .offset:         192
        .size:           2
        .value_kind:     hidden_group_size_z
      - .offset:         194
        .size:           2
        .value_kind:     hidden_remainder_x
      - .offset:         196
        .size:           2
        .value_kind:     hidden_remainder_y
      - .offset:         198
        .size:           2
        .value_kind:     hidden_remainder_z
      - .offset:         216
        .size:           8
        .value_kind:     hidden_global_offset_x
      - .offset:         224
        .size:           8
        .value_kind:     hidden_global_offset_y
      - .offset:         232
        .size:           8
        .value_kind:     hidden_global_offset_z
      - .offset:         240
        .size:           2
        .value_kind:     hidden_grid_dims
      - .offset:         264
        .size:           8
        .value_kind:     hidden_multigrid_sync_arg
      - .offset:         296
        .size:           4
        .value_kind:     hidden_dynamic_lds_size
    .group_segment_fixed_size: 0
    .kernarg_segment_align: 8
    .kernarg_segment_size: 432
    .language:       OpenCL C
    .language_version:
      - 2
      - 0
    .max_flat_workgroup_size: 512
    .name:           _Z14fwd_megakernel4Args
    .private_segment_fixed_size: 0
    .sgpr_count:     104
    .sgpr_spill_count: 89
    .symbol:         _Z14fwd_megakernel4Args.kd
    .uniform_work_group_size: 1
    .uses_dynamic_stack: false
    .vgpr_count:     256
    .vgpr_spill_count: 0
    .wavefront_size: 64
